# v16 plus residual GEMM tail pieces skip the LDS fragment reads of halves they do not own
# speedup vs baseline: 1.0019x; 1.0019x over previous
; #define PG8_STAGE(bufoff, gbase, voff) do { _Pragma("unroll") for (int _i = 0; _i < 2; ++_i) \
;         __builtin_amdgcn_global_load_lds((const unsigned*)((const char*)(gbase) + (voff)[_i]), (PG8_LAS unsigned*)(lds + (bufoff) + ldsw + _i * 8192), 16, 0, 0); } while (0)
; #define PG8_LDA(dst, b, h) do { _Pragma("unroll") for (int m = 0; m < 4; ++m) _Pragma("unroll") for (int k = 0; k < 2; ++k) dst[m][k] = *(const PG8_LAS bf16x8*)(lds + PG8_SA(b, h) + aoff + m * 2048 + k * 1024); } while (0)
; #define PG8_LDB(dst, b, h) do { _Pragma("unroll") for (int n = 0; n < 2; ++n) _Pragma("unroll") for (int k = 0; k < 2; ++k) dst[n][k] = *(const PG8_LAS bf16x8*)(lds + PG8_SB(b, h) + boff + n * 2048 + k * 1024); } while (0)
; #define PG8_MMA(ai, bj, At, Bt) do { __builtin_amdgcn_s_setprio(1); _Pragma("unroll") for (int m = 0; m < 4; ++m) _Pragma("unroll") for (int n = 0; n < 2; ++n) _Pragma("unroll") for (int k = 0; k < 2; ++k) \
;         acc[ai][bj][m][n] = __builtin_amdgcn_mfma_f32_16x16x32_bf16(Bt[n][k], At[m][k], acc[ai][bj][m][n], 0, 0, 0); __builtin_amdgcn_s_setprio(0); } while (0)
; #define PG8_WAIT_V(n) asm volatile("s_waitcnt vmcnt(" #n ")" ::: "memory")
; #define PG8_WAIT_L(n) asm volatile("s_waitcnt lgkmcnt(" #n ")" ::: "memory")
; #define PG8_BAR __builtin_amdgcn_s_barrier()
; #define PG8_SCHED __builtin_amdgcn_sched_barrier(0)
; template <class Epi, class Sched, bool ALIGN_EPI = false, bool SP2 = false>
; __device__ __forceinline__ void gemm_phase(PG8_LAS unsigned char* lds, const Gemm g, const Sched& S, const Epi& E) {
;     ...
;             PG8_LDB(B0, 0, 0); PG8_LDB(B1, 0, 1); PG8_SCHED; PG8_LDA(At, 0, 0); PG8_STAGE(PG8_SA(1, 1), a1 + hstep, voffA);
;             PG8_WAIT_V(8); PG8_WAIT_L(0); PG8_BAR; PG8_MMA(0, 0, At, B0); if (doB1) PG8_MMA(0, 1, At, B1); PG8_BAR; PG8_SCHED;
;             PG8_LDA(At, 0, 1); PG8_STAGE(PG8_SB(0, 0), b2, voffB); PG8_STAGE(PG8_SB(0, 1), b2 + hstep, voffB); PG8_STAGE(PG8_SA(0, 0), a2, voffA);
;             PG8_WAIT_V(8); PG8_WAIT_L(0); PG8_BAR; if (doA1) { PG8_MMA(1, 0, At, B0); if (doB1) PG8_MMA(1, 1, At, B1); } PG8_BAR; PG8_SCHED;
.LBB0_847:
	v_add_u32_e32 v128, 0x10000, v234
	ds_read_b128 v[146:149], v128
	ds_read_b128 v[150:153], v128 offset:1024
	ds_read_b128 v[154:157], v128 offset:2048
	ds_read_b128 v[158:161], v128 offset:3072
	s_andn2_b64 vcc, exec, s[72:73]
	s_cbranch_vccnz .Ltl_s1
	v_add_u32_e32 v128, 0x14000, v234
	ds_read_b128 v[130:133], v128
	ds_read_b128 v[134:137], v128 offset:1024
	ds_read_b128 v[138:141], v128 offset:2048
	ds_read_b128 v[142:145], v128 offset:3072
.Ltl_s1:
	v_lshl_add_u64 v[214:215], s[60:61], 0, v[206:207]
	s_add_i32 m0, s50, 0xc000
	s_waitcnt lgkmcnt(0)
	ds_read_b128 v[186:189], v235
	ds_read_b128 v[190:193], v235 offset:1024
	ds_read_b128 v[178:181], v235 offset:2048
	ds_read_b128 v[182:185], v235 offset:3072
	ds_read_b128 v[170:173], v235 offset:4096
	ds_read_b128 v[174:177], v235 offset:5120
	ds_read_b128 v[162:165], v235 offset:6144
	ds_read_b128 v[166:169], v235 offset:7168
	global_load_lds_dwordx4 v[214:215], off
	v_lshl_add_u64 v[214:215], s[60:61], 0, v[208:209]
	s_add_i32 m0, s50, 0xe000
	s_nop 0
	global_load_lds_dwordx4 v[214:215], off
	s_waitcnt vmcnt(8)
	s_waitcnt lgkmcnt(0)
	s_barrier
	s_setprio 1
	s_waitcnt lgkmcnt(0)
	v_mfma_f32_16x16x32_bf16 v[124:127], v[146:149], v[186:189], v[124:127]
	v_mfma_f32_16x16x32_bf16 v[120:123], v[154:157], v[186:189], v[120:123]
	v_mfma_f32_16x16x32_bf16 v[116:119], v[146:149], v[178:181], v[116:119]
	v_mfma_f32_16x16x32_bf16 v[112:115], v[154:157], v[178:181], v[112:115]
	v_mfma_f32_16x16x32_bf16 v[92:95], v[146:149], v[170:173], v[92:95]
	v_mfma_f32_16x16x32_bf16 v[88:91], v[154:157], v[170:173], v[88:91]
	v_mfma_f32_16x16x32_bf16 v[84:87], v[146:149], v[162:165], v[84:87]
	v_mfma_f32_16x16x32_bf16 v[80:83], v[154:157], v[162:165], v[80:83]
	v_mfma_f32_16x16x32_bf16 v[124:127], v[150:153], v[190:193], v[124:127]
	v_mfma_f32_16x16x32_bf16 v[120:123], v[158:161], v[190:193], v[120:123]
	v_mfma_f32_16x16x32_bf16 v[116:119], v[150:153], v[182:185], v[116:119]
	v_mfma_f32_16x16x32_bf16 v[112:115], v[158:161], v[182:185], v[112:115]
	v_mfma_f32_16x16x32_bf16 v[92:95], v[150:153], v[174:177], v[92:95]
	v_mfma_f32_16x16x32_bf16 v[88:91], v[158:161], v[174:177], v[88:91]
	v_mfma_f32_16x16x32_bf16 v[84:87], v[150:153], v[166:169], v[84:87]
	v_mfma_f32_16x16x32_bf16 v[80:83], v[158:161], v[166:169], v[80:83]
	s_setprio 0
	v_cndmask_b32_e64 v128, 0, 1, s[72:73]
	v_cmp_ne_u32_e64 s[8:9], 1, v128
	s_andn2_b64 vcc, exec, s[72:73]
	s_cbranch_vccnz .LBB0_849
	s_setprio 1
	v_mfma_f32_16x16x32_bf16 v[108:111], v[130:133], v[186:189], v[108:111]
	v_mfma_f32_16x16x32_bf16 v[104:107], v[138:141], v[186:189], v[104:107]
	v_mfma_f32_16x16x32_bf16 v[100:103], v[130:133], v[178:181], v[100:103]
	v_mfma_f32_16x16x32_bf16 v[96:99], v[138:141], v[178:181], v[96:99]
	v_mfma_f32_16x16x32_bf16 v[76:79], v[130:133], v[170:173], v[76:79]
	v_mfma_f32_16x16x32_bf16 v[72:75], v[138:141], v[170:173], v[72:75]
	v_mfma_f32_16x16x32_bf16 v[68:71], v[130:133], v[162:165], v[68:71]
	v_mfma_f32_16x16x32_bf16 v[64:67], v[138:141], v[162:165], v[64:67]
	v_mfma_f32_16x16x32_bf16 v[108:111], v[134:137], v[190:193], v[108:111]
	v_mfma_f32_16x16x32_bf16 v[104:107], v[142:145], v[190:193], v[104:107]
	v_mfma_f32_16x16x32_bf16 v[100:103], v[134:137], v[182:185], v[100:103]
	v_mfma_f32_16x16x32_bf16 v[96:99], v[142:145], v[182:185], v[96:99]
	v_mfma_f32_16x16x32_bf16 v[76:79], v[134:137], v[174:177], v[76:79]
	v_mfma_f32_16x16x32_bf16 v[72:75], v[142:145], v[174:177], v[72:75]
	v_mfma_f32_16x16x32_bf16 v[68:71], v[134:137], v[166:169], v[68:71]
	v_mfma_f32_16x16x32_bf16 v[64:67], v[142:145], v[166:169], v[64:67]
	s_setprio 0
.LBB0_849:
	s_add_u32 s10, s60, 0x80
	s_addc_u32 s11, s61, 0
	s_cmp_eq_u32 s55, s25
	s_cselect_b32 s75, s77, s11
	s_cselect_b32 s74, s76, s10
	s_cselect_b32 s11, s63, s91
	s_cselect_b32 s10, s62, s90
	s_barrier
	s_andn2_b64 vcc, exec, s[52:53]
	s_mov_b32 m0, s51
	v_lshl_add_u64 v[214:215], s[10:11], 0, v[196:197]
	v_lshl_add_u64 v[216:217], s[10:11], 0, v[200:201]
	s_add_u32 s10, s10, s88
	s_cbranch_vccnz .Ltl_s2
	ds_read_b128 v[186:189], v235 offset:16384
	ds_read_b128 v[190:193], v235 offset:17408
	ds_read_b128 v[178:181], v235 offset:18432
	ds_read_b128 v[182:185], v235 offset:19456
	ds_read_b128 v[170:173], v235 offset:20480
	ds_read_b128 v[174:177], v235 offset:21504
	ds_read_b128 v[162:165], v235 offset:22528
	ds_read_b128 v[166:169], v235 offset:23552
; #define PG8_STAGE(bufoff, gbase, voff) do { _Pragma("unroll") for (int _i = 0; _i < 2; ++_i) \
;         __builtin_amdgcn_global_load_lds((const unsigned*)((const char*)(gbase) + (voff)[_i]), (PG8_LAS unsigned*)(lds + (bufoff) + ldsw + _i * 8192), 16, 0, 0); } while (0)
; #define PG8_LDA(dst, b, h) do { _Pragma("unroll") for (int m = 0; m < 4; ++m) _Pragma("unroll") for (int k = 0; k < 2; ++k) dst[m][k] = *(const PG8_LAS bf16x8*)(lds + PG8_SA(b, h) + aoff + m * 2048 + k * 1024); } while (0)
; #define PG8_LDB(dst, b, h) do { _Pragma("unroll") for (int n = 0; n < 2; ++n) _Pragma("unroll") for (int k = 0; k < 2; ++k) dst[n][k] = *(const PG8_LAS bf16x8*)(lds + PG8_SB(b, h) + boff + n * 2048 + k * 1024); } while (0)
; #define PG8_MMA(ai, bj, At, Bt) do { __builtin_amdgcn_s_setprio(1); _Pragma("unroll") for (int m = 0; m < 4; ++m) _Pragma("unroll") for (int n = 0; n < 2; ++n) _Pragma("unroll") for (int k = 0; k < 2; ++k) \
;         acc[ai][bj][m][n] = __builtin_amdgcn_mfma_f32_16x16x32_bf16(Bt[n][k], At[m][k], acc[ai][bj][m][n], 0, 0, 0); __builtin_amdgcn_s_setprio(0); } while (0)
; #define PG8_WAIT_V(n) asm volatile("s_waitcnt vmcnt(" #n ")" ::: "memory")
; #define PG8_WAIT_L(n) asm volatile("s_waitcnt lgkmcnt(" #n ")" ::: "memory")
; #define PG8_BAR __builtin_amdgcn_s_barrier()
; #define PG8_SCHED __builtin_amdgcn_sched_barrier(0)
; template <class Epi, class Sched, bool ALIGN_EPI = false, bool SP2 = false>
; __device__ __forceinline__ void gemm_phase(PG8_LAS unsigned char* lds, const Gemm g, const Sched& S, const Epi& E) {
;     ...
;             PG8_LDA(At, 0, 1); PG8_STAGE(PG8_SB(0, 0), b2, voffB); PG8_STAGE(PG8_SB(0, 1), b2 + hstep, voffB); PG8_STAGE(PG8_SA(0, 0), a2, voffA);
;             PG8_WAIT_V(8); PG8_WAIT_L(0); PG8_BAR; if (doA1) { PG8_MMA(1, 0, At, B0); if (doB1) PG8_MMA(1, 1, At, B1); } PG8_BAR; PG8_SCHED;
;             PG8_LDB(B0, 1, 0); PG8_LDB(B1, 1, 1); PG8_SCHED; PG8_LDA(At, 1, 0); PG8_STAGE(PG8_SA(0, 1), a2 + hstep, voffA);
;             PG8_WAIT_V(8); PG8_WAIT_L(0); PG8_BAR; PG8_MMA(0, 0, At, B0); if (doB1) PG8_MMA(0, 1, At, B1); PG8_BAR; PG8_SCHED;
.Ltl_s2:
	global_load_lds_dwordx4 v[214:215], off
	s_mov_b32 m0, s35
	s_addc_u32 s11, s11, 0
	global_load_lds_dwordx4 v[216:217], off
	v_lshl_add_u64 v[218:219], s[10:11], 0, v[196:197]
	s_mov_b32 m0, s70
	v_lshl_add_u64 v[220:221], s[10:11], 0, v[200:201]
	global_load_lds_dwordx4 v[218:219], off
	s_mov_b32 m0, s14
	v_lshl_add_u64 v[222:223], s[74:75], 0, v[194:195]
	global_load_lds_dwordx4 v[220:221], off
	s_mov_b32 m0, s50
	v_lshl_add_u64 v[224:225], s[74:75], 0, v[198:199]
	global_load_lds_dwordx4 v[222:223], off
	s_mov_b32 m0, s15
	v_cndmask_b32_e64 v128, 0, 1, s[52:53]
	global_load_lds_dwordx4 v[224:225], off
	s_waitcnt vmcnt(8)
	s_waitcnt lgkmcnt(0)
	v_cmp_ne_u32_e64 s[10:11], 1, v128
	s_andn2_b64 vcc, exec, s[52:53]
	s_barrier
	s_cbranch_vccnz .LBB0_852
	s_setprio 1
	s_waitcnt lgkmcnt(0)
	v_mfma_f32_16x16x32_bf16 v[60:63], v[146:149], v[186:189], v[60:63]
	v_mfma_f32_16x16x32_bf16 v[56:59], v[154:157], v[186:189], v[56:59]
	v_mfma_f32_16x16x32_bf16 v[44:47], v[146:149], v[178:181], v[44:47]
	v_mfma_f32_16x16x32_bf16 v[40:43], v[154:157], v[178:181], v[40:43]
	v_mfma_f32_16x16x32_bf16 v[28:31], v[146:149], v[170:173], v[28:31]
	v_mfma_f32_16x16x32_bf16 v[24:27], v[154:157], v[170:173], v[24:27]
	v_mfma_f32_16x16x32_bf16 v[12:15], v[146:149], v[162:165], v[12:15]
	v_mfma_f32_16x16x32_bf16 v[8:11], v[154:157], v[162:165], v[8:11]
	v_mfma_f32_16x16x32_bf16 v[60:63], v[150:153], v[190:193], v[60:63]
	v_mfma_f32_16x16x32_bf16 v[56:59], v[158:161], v[190:193], v[56:59]
	v_mfma_f32_16x16x32_bf16 v[44:47], v[150:153], v[182:185], v[44:47]
	v_mfma_f32_16x16x32_bf16 v[40:43], v[158:161], v[182:185], v[40:43]
	v_mfma_f32_16x16x32_bf16 v[28:31], v[150:153], v[174:177], v[28:31]
	v_mfma_f32_16x16x32_bf16 v[24:27], v[158:161], v[174:177], v[24:27]
	v_mfma_f32_16x16x32_bf16 v[12:15], v[150:153], v[166:169], v[12:15]
	v_mfma_f32_16x16x32_bf16 v[8:11], v[158:161], v[166:169], v[8:11]
	s_setprio 0
	s_and_b64 vcc, exec, s[8:9]
	s_cbranch_vccnz .LBB0_852
	s_setprio 1
	v_mfma_f32_16x16x32_bf16 v[52:55], v[130:133], v[186:189], v[52:55]
	v_mfma_f32_16x16x32_bf16 v[48:51], v[138:141], v[186:189], v[48:51]
	v_mfma_f32_16x16x32_bf16 v[36:39], v[130:133], v[178:181], v[36:39]
	v_mfma_f32_16x16x32_bf16 v[32:35], v[138:141], v[178:181], v[32:35]
	v_mfma_f32_16x16x32_bf16 v[20:23], v[130:133], v[170:173], v[20:23]
	v_mfma_f32_16x16x32_bf16 v[16:19], v[138:141], v[170:173], v[16:19]
	v_mfma_f32_16x16x32_bf16 v[4:7], v[130:133], v[162:165], v[4:7]
	v_mfma_f32_16x16x32_bf16 v[0:3], v[138:141], v[162:165], v[0:3]
	v_mfma_f32_16x16x32_bf16 v[52:55], v[134:137], v[190:193], v[52:55]
	v_mfma_f32_16x16x32_bf16 v[48:51], v[142:145], v[190:193], v[48:51]
	v_mfma_f32_16x16x32_bf16 v[36:39], v[134:137], v[182:185], v[36:39]
	v_mfma_f32_16x16x32_bf16 v[32:35], v[142:145], v[182:185], v[32:35]
	v_mfma_f32_16x16x32_bf16 v[20:23], v[134:137], v[174:177], v[20:23]
	v_mfma_f32_16x16x32_bf16 v[16:19], v[142:145], v[174:177], v[16:19]
	v_mfma_f32_16x16x32_bf16 v[4:7], v[134:137], v[166:169], v[4:7]
	v_mfma_f32_16x16x32_bf16 v[0:3], v[142:145], v[166:169], v[0:3]
	s_setprio 0
.LBB0_852:
	s_barrier
	v_add_u32_e32 v128, 0x18000, v234
	ds_read_b128 v[146:149], v128
	ds_read_b128 v[150:153], v128 offset:1024
	ds_read_b128 v[154:157], v128 offset:2048
	ds_read_b128 v[158:161], v128 offset:3072
	s_andn2_b64 vcc, exec, s[72:73]
	s_cbranch_vccnz .Ltl_s3
	v_add_u32_e32 v128, 0x1c000, v234
	ds_read_b128 v[130:133], v128
	ds_read_b128 v[134:137], v128 offset:1024
	ds_read_b128 v[138:141], v128 offset:2048
	ds_read_b128 v[142:145], v128 offset:3072
.Ltl_s3:
	s_add_u32 s74, s74, s88
	s_addc_u32 s75, s75, 0
	s_mov_b32 m0, s71
	v_lshl_add_u64 v[240:241], s[74:75], 0, v[194:195]
	s_waitcnt lgkmcnt(0)
	ds_read_b128 v[186:189], v235 offset:32768
	ds_read_b128 v[190:193], v235 offset:33792
	ds_read_b128 v[178:181], v235 offset:34816
	ds_read_b128 v[182:185], v235 offset:35840
	ds_read_b128 v[170:173], v235 offset:36864
	ds_read_b128 v[174:177], v235 offset:37888
	ds_read_b128 v[162:165], v235 offset:38912
	ds_read_b128 v[166:169], v235 offset:39936
	global_load_lds_dwordx4 v[240:241], off
	v_lshl_add_u64 v[240:241], s[74:75], 0, v[198:199]
	s_mov_b32 m0, s33
	s_nop 0
	global_load_lds_dwordx4 v[240:241], off
	s_waitcnt vmcnt(8)
	s_waitcnt lgkmcnt(0)
	s_barrier
	s_setprio 1
	s_waitcnt lgkmcnt(0)
	v_mfma_f32_16x16x32_bf16 v[124:127], v[146:149], v[186:189], v[124:127]
	v_mfma_f32_16x16x32_bf16 v[120:123], v[154:157], v[186:189], v[120:123]
	v_mfma_f32_16x16x32_bf16 v[116:119], v[146:149], v[178:181], v[116:119]
	v_mfma_f32_16x16x32_bf16 v[112:115], v[154:157], v[178:181], v[112:115]
	v_mfma_f32_16x16x32_bf16 v[92:95], v[146:149], v[170:173], v[92:95]
	v_mfma_f32_16x16x32_bf16 v[88:91], v[154:157], v[170:173], v[88:91]
	v_mfma_f32_16x16x32_bf16 v[84:87], v[146:149], v[162:165], v[84:87]
	v_mfma_f32_16x16x32_bf16 v[80:83], v[154:157], v[162:165], v[80:83]
	v_mfma_f32_16x16x32_bf16 v[124:127], v[150:153], v[190:193], v[124:127]
	v_mfma_f32_16x16x32_bf16 v[120:123], v[158:161], v[190:193], v[120:123]
	v_mfma_f32_16x16x32_bf16 v[116:119], v[150:153], v[182:185], v[116:119]
	v_mfma_f32_16x16x32_bf16 v[112:115], v[158:161], v[182:185], v[112:115]
	v_mfma_f32_16x16x32_bf16 v[92:95], v[150:153], v[174:177], v[92:95]
	v_mfma_f32_16x16x32_bf16 v[88:91], v[158:161], v[174:177], v[88:91]
	v_mfma_f32_16x16x32_bf16 v[84:87], v[150:153], v[166:169], v[84:87]
	v_mfma_f32_16x16x32_bf16 v[80:83], v[158:161], v[166:169], v[80:83]
	s_setprio 0
	s_and_b64 vcc, exec, s[8:9]
	s_cbranch_vccnz .LBB0_854
	s_setprio 1
	v_mfma_f32_16x16x32_bf16 v[108:111], v[130:133], v[186:189], v[108:111]
	v_mfma_f32_16x16x32_bf16 v[104:107], v[138:141], v[186:189], v[104:107]
	v_mfma_f32_16x16x32_bf16 v[100:103], v[130:133], v[178:181], v[100:103]
	v_mfma_f32_16x16x32_bf16 v[96:99], v[138:141], v[178:181], v[96:99]
	v_mfma_f32_16x16x32_bf16 v[76:79], v[130:133], v[170:173], v[76:79]
	v_mfma_f32_16x16x32_bf16 v[72:75], v[138:141], v[170:173], v[72:75]
	v_mfma_f32_16x16x32_bf16 v[68:71], v[130:133], v[162:165], v[68:71]
	v_mfma_f32_16x16x32_bf16 v[64:67], v[138:141], v[162:165], v[64:67]
	v_mfma_f32_16x16x32_bf16 v[108:111], v[134:137], v[190:193], v[108:111]
	v_mfma_f32_16x16x32_bf16 v[104:107], v[142:145], v[190:193], v[104:107]
	v_mfma_f32_16x16x32_bf16 v[100:103], v[134:137], v[182:185], v[100:103]
	v_mfma_f32_16x16x32_bf16 v[96:99], v[142:145], v[182:185], v[96:99]
	v_mfma_f32_16x16x32_bf16 v[76:79], v[134:137], v[174:177], v[76:79]
	v_mfma_f32_16x16x32_bf16 v[72:75], v[142:145], v[174:177], v[72:75]
	v_mfma_f32_16x16x32_bf16 v[68:71], v[134:137], v[166:169], v[68:71]
	v_mfma_f32_16x16x32_bf16 v[64:67], v[142:145], v[166:169], v[64:67]
	s_setprio 0
; #define PG8_STAGE(bufoff, gbase, voff) do { _Pragma("unroll") for (int _i = 0; _i < 2; ++_i) \
;         __builtin_amdgcn_global_load_lds((const unsigned*)((const char*)(gbase) + (voff)[_i]), (PG8_LAS unsigned*)(lds + (bufoff) + ldsw + _i * 8192), 16, 0, 0); } while (0)
; #define PG8_LDA(dst, b, h) do { _Pragma("unroll") for (int m = 0; m < 4; ++m) _Pragma("unroll") for (int k = 0; k < 2; ++k) dst[m][k] = *(const PG8_LAS bf16x8*)(lds + PG8_SA(b, h) + aoff + m * 2048 + k * 1024); } while (0)
; #define PG8_MMA(ai, bj, At, Bt) do { __builtin_amdgcn_s_setprio(1); _Pragma("unroll") for (int m = 0; m < 4; ++m) _Pragma("unroll") for (int n = 0; n < 2; ++n) _Pragma("unroll") for (int k = 0; k < 2; ++k) \
;         acc[ai][bj][m][n] = __builtin_amdgcn_mfma_f32_16x16x32_bf16(Bt[n][k], At[m][k], acc[ai][bj][m][n], 0, 0, 0); __builtin_amdgcn_s_setprio(0); } while (0)
; #define PG8_WAIT_V(n) asm volatile("s_waitcnt vmcnt(" #n ")" ::: "memory")
; #define PG8_WAIT_L(n) asm volatile("s_waitcnt lgkmcnt(" #n ")" ::: "memory")
; #define PG8_BAR __builtin_amdgcn_s_barrier()
; #define PG8_SCHED __builtin_amdgcn_sched_barrier(0)
; template <class Epi, class Sched, bool ALIGN_EPI = false, bool SP2 = false>
; __device__ __forceinline__ void gemm_phase(PG8_LAS unsigned char* lds, const Gemm g, const Sched& S, const Epi& E) {
;     ...
;             PG8_LDA(At, 1, 1); PG8_STAGE(PG8_SB(1, 0), b3, voffB); PG8_STAGE(PG8_SB(1, 1), b3 + hstep, voffB); PG8_STAGE(PG8_SA(1, 0), a3, voffA);
;             PG8_WAIT_V(8); PG8_WAIT_L(0); PG8_BAR; if (doA1) { PG8_MMA(1, 0, At, B0); if (doB1) PG8_MMA(1, 1, At, B1); } PG8_BAR; PG8_SCHED;
.LBB0_854:
	s_barrier
	s_andn2_b64 vcc, exec, s[52:53]
	s_mov_b32 m0, s54
	v_lshl_add_u64 v[214:215], v[214:215], 0, s[30:31]
	s_cbranch_vccnz .Ltl_s4
	ds_read_b128 v[186:189], v235 offset:49152
	ds_read_b128 v[190:193], v235 offset:50176
	ds_read_b128 v[178:181], v235 offset:51200
	ds_read_b128 v[182:185], v235 offset:52224
	ds_read_b128 v[170:173], v235 offset:53248
	ds_read_b128 v[174:177], v235 offset:54272
	ds_read_b128 v[162:165], v235 offset:55296
	ds_read_b128 v[166:169], v235 offset:56320
.Ltl_s4:
	global_load_lds_dwordx4 v[214:215], off
	v_lshl_add_u64 v[214:215], v[216:217], 0, s[30:31]
	s_mov_b32 m0, s1
	s_and_b64 vcc, exec, s[10:11]
	global_load_lds_dwordx4 v[214:215], off
	v_lshl_add_u64 v[214:215], v[218:219], 0, s[30:31]
	s_mov_b32 m0, s16
	s_nop 0
	global_load_lds_dwordx4 v[214:215], off
	v_lshl_add_u64 v[214:215], v[220:221], 0, s[30:31]
	s_mov_b32 m0, s38
	s_nop 0
	global_load_lds_dwordx4 v[214:215], off
	v_lshl_add_u64 v[214:215], v[222:223], 0, s[30:31]
	s_mov_b32 m0, s0
	s_nop 0
	global_load_lds_dwordx4 v[214:215], off
	v_lshl_add_u64 v[214:215], v[224:225], 0, s[30:31]
	s_mov_b32 m0, s27
	s_nop 0
	global_load_lds_dwordx4 v[214:215], off
	s_waitcnt vmcnt(8)
	s_waitcnt lgkmcnt(0)
	s_barrier
	s_cbranch_vccnz .LBB0_846
	s_setprio 1
	s_waitcnt lgkmcnt(0)
	v_mfma_f32_16x16x32_bf16 v[60:63], v[146:149], v[186:189], v[60:63]
	v_mfma_f32_16x16x32_bf16 v[56:59], v[154:157], v[186:189], v[56:59]
	v_mfma_f32_16x16x32_bf16 v[44:47], v[146:149], v[178:181], v[44:47]
	v_mfma_f32_16x16x32_bf16 v[40:43], v[154:157], v[178:181], v[40:43]
	v_mfma_f32_16x16x32_bf16 v[28:31], v[146:149], v[170:173], v[28:31]
	v_mfma_f32_16x16x32_bf16 v[24:27], v[154:157], v[170:173], v[24:27]
	v_mfma_f32_16x16x32_bf16 v[12:15], v[146:149], v[162:165], v[12:15]
	v_mfma_f32_16x16x32_bf16 v[8:11], v[154:157], v[162:165], v[8:11]
	v_mfma_f32_16x16x32_bf16 v[60:63], v[150:153], v[190:193], v[60:63]
	v_mfma_f32_16x16x32_bf16 v[56:59], v[158:161], v[190:193], v[56:59]
	v_mfma_f32_16x16x32_bf16 v[44:47], v[150:153], v[182:185], v[44:47]
	v_mfma_f32_16x16x32_bf16 v[40:43], v[158:161], v[182:185], v[40:43]
	v_mfma_f32_16x16x32_bf16 v[28:31], v[150:153], v[174:177], v[28:31]
	v_mfma_f32_16x16x32_bf16 v[24:27], v[158:161], v[174:177], v[24:27]
	v_mfma_f32_16x16x32_bf16 v[12:15], v[150:153], v[166:169], v[12:15]
	v_mfma_f32_16x16x32_bf16 v[8:11], v[158:161], v[166:169], v[8:11]
	s_setprio 0
	s_and_b64 vcc, exec, s[8:9]
	s_cbranch_vccnz .LBB0_846
	s_setprio 1
	v_mfma_f32_16x16x32_bf16 v[52:55], v[130:133], v[186:189], v[52:55]
	v_mfma_f32_16x16x32_bf16 v[48:51], v[138:141], v[186:189], v[48:51]
	v_mfma_f32_16x16x32_bf16 v[36:39], v[130:133], v[178:181], v[36:39]
	v_mfma_f32_16x16x32_bf16 v[32:35], v[138:141], v[178:181], v[32:35]
	v_mfma_f32_16x16x32_bf16 v[20:23], v[130:133], v[170:173], v[20:23]
	v_mfma_f32_16x16x32_bf16 v[16:19], v[138:141], v[170:173], v[16:19]
	v_mfma_f32_16x16x32_bf16 v[4:7], v[130:133], v[162:165], v[4:7]
	v_mfma_f32_16x16x32_bf16 v[0:3], v[138:141], v[162:165], v[0:3]
	v_mfma_f32_16x16x32_bf16 v[52:55], v[134:137], v[190:193], v[52:55]
	v_mfma_f32_16x16x32_bf16 v[48:51], v[142:145], v[190:193], v[48:51]
	v_mfma_f32_16x16x32_bf16 v[36:39], v[134:137], v[182:185], v[36:39]
	v_mfma_f32_16x16x32_bf16 v[32:35], v[142:145], v[182:185], v[32:35]
	v_mfma_f32_16x16x32_bf16 v[20:23], v[134:137], v[174:177], v[20:23]
	v_mfma_f32_16x16x32_bf16 v[16:19], v[142:145], v[174:177], v[16:19]
	v_mfma_f32_16x16x32_bf16 v[4:7], v[134:137], v[166:169], v[4:7]
	v_mfma_f32_16x16x32_bf16 v[0:3], v[142:145], v[166:169], v[0:3]
	s_setprio 0
	s_branch .LBB0_846
